# v11: vtshift guarded by grid==256
# speedup vs baseline: 1.0005x; 1.0005x over previous
; #define ws (KP()->ws)
;     __host__ __device__ bool next(int i, Unit& u) const {
;         const long L = (long)i * G + c; if (L >= nwg) return false;
;         int wgid = (int)L; { const int q = nwg / NXCD, r = nwg % NXCD, xcd = wgid % NXCD, off = wgid / NXCD; wgid = (xcd < r ? xcd * (q + 1) : r * (q + 1) + (xcd - r) * q) + off; }
; __global__ void __launch_bounds__(NTHREADS, 2) trunk_fwd(Params p) {
;     ...
;         {
;             const int vrows = (kind == 2) ? 256 : 1024;
;             pg8::Gemm g{wl + W_IN / 2 + (size_t)(nqkv - vrows) * DM, HB, vrows, MTOK, DM}; pg8::StaticOrder S; S.init(vrows, MTOK, G, (int)blockIdx.x);
;             pg8::EpiVT E{ws + WS_VT, nkv, (kind == 2) ? 128 : 0, rsq1, bias1 + (nqkv - vrows), 3072};
;             pg8::gemm_phase<pg8::EpiVT, pg8::StaticOrder, true, true>(lds, g, S, E, wave_s);
.LBB0_306:
	s_cmpk_eq_u32 s42, 0x100
	s_cselect_b32 s98, 0x80, 0
	s_xor_b32 s98, s2, s98
	s_mov_b64 s[4:5], s[0:1]
	s_load_dwordx2 s[10:11], s[4:5], 0x90
	s_mov_b64 s[4:5], s[0:1]
	s_load_dwordx2 s[4:5], s[4:5], 0x90
	s_lshl_b32 s6, s41, 7
	v_mbcnt_lo_u32_b32 v0, -1, 0
	v_mbcnt_hi_u32_b32 v0, -1, v0
	s_cmp_lt_i32 s98, s6
	v_add_u32_e32 v2, s94, v0
	s_cselect_b64 s[12:13], -1, 0
	s_cmp_ge_i32 s98, s6
	v_readfirstlane_b32 s7, v2
	s_cbranch_scc1 .LBB0_312
	v_readlane_b32 s18, v242, 5
	v_readlane_b32 s19, v242, 6
	s_mov_b64 s[14:15], -1
	s_and_b64 vcc, exec, s[18:19]
	s_cbranch_vccz .LBB0_309
	s_and_b64 s[14:15], s[16:17], exec
	s_cselect_b32 s14, 4, 6
	v_readlane_b32 s15, v242, 30
	s_lshl_b32 s18, s15, s14
	s_mov_b64 s[14:15], 0
